# P3 qknorm: KV row accessed as 8 row-contiguous 1-KiB loads/stores per wave with a per-wave LDS transpose (was 16 B per lane at 128-B lane stride: 64 partial lines per instruction)
# speedup vs baseline: 1.0080x; 1.0080x over previous
.LBB0_272:
	s_cmp_lt_i32 s98, 4
	s_cselect_b64 s[0:1], -1, 0
	s_cmp_gt_i32 s99, 3
	s_cselect_b64 s[4:5], -1, 0
	s_and_b64 s[0:1], s[0:1], s[4:5]
	s_andn2_b64 vcc, exec, s[0:1]
	s_cbranch_vccnz .LBB0_288
	v_mbcnt_hi_u32_b32 v2, -1, v147
	v_readlane_b32 s0, v255, 3
	v_mov_b32_e32 v3, v2
	s_cmpk_gt_i32 s0, 0x7fff
	v_readlane_b32 s1, v255, 4
	s_cbranch_scc1 .LBB0_276
	v_and_b32_e32 v7, 3, v3
	v_ashrrev_i32_e32 v9, 2, v3
	v_lshlrev_b32_e32 v64, 4, v3
	v_lshlrev_b32_e32 v3, 6, v3
	s_movk_i32 s0, 0xc0
	v_and_b32_e32 v8, 64, v3
	v_and_b32_e32 v3, 64, v2
	v_mul_lo_u32 v10, v9, s0
	v_lshlrev_b32_e32 v62, 5, v7
	v_lshlrev_b32_e32 v6, 3, v7
	v_lshlrev_b32_e32 v11, 7, v7
	v_lshlrev_b32_e32 v12, 4, v7
	v_cmp_gt_u32_e64 s[0:1], 2, v7
	v_cmp_lt_u32_e64 s[4:5], 1, v7
	v_add_u32_e32 v3, 64, v3
	v_xor_b32_e32 v7, 1, v2
	v_cmp_lt_i32_e32 vcc, v7, v3
	s_add_u32 s22, s96, 0x7a00000
	s_addc_u32 s23, s97, 0
	v_cndmask_b32_e32 v7, v2, v7, vcc
	v_lshlrev_b32_e32 v63, 2, v7
	v_xor_b32_e32 v7, 2, v2
	v_cmp_lt_i32_e32 vcc, v7, v3
	s_add_u32 s24, s96, 0x7c00000
	v_readlane_b32 s7, v255, 2
	v_cndmask_b32_e32 v7, v2, v7, vcc
	v_lshlrev_b32_e32 v108, 2, v7
	v_xor_b32_e32 v7, 4, v2
	v_cmp_lt_i32_e32 vcc, v7, v3
	s_addc_u32 s25, s97, 0
	s_lshl_b32 s6, s2, 8
	v_cndmask_b32_e32 v7, v2, v7, vcc
	v_lshlrev_b32_e32 v109, 2, v7
	v_xor_b32_e32 v7, 8, v2
	v_cmp_lt_i32_e32 vcc, v7, v3
	s_lshl_b32 s7, s7, 5
	s_add_i32 s26, s6, s7
	v_cndmask_b32_e32 v7, v2, v7, vcc
	v_lshlrev_b32_e32 v110, 2, v7
	v_xor_b32_e32 v7, 16, v2
	v_cmp_lt_i32_e32 vcc, v7, v3
	v_readlane_b32 s6, v255, 3
	v_mov_b32_e32 v65, 0
	v_cndmask_b32_e32 v7, v2, v7, vcc
	v_lshlrev_b32_e32 v111, 2, v7
	v_xor_b32_e32 v7, 32, v2
	v_cmp_lt_i32_e32 vcc, v7, v3
	v_readlane_b32 s7, v255, 4
	s_mov_b32 s20, s6
	v_cndmask_b32_e32 v2, v2, v7, vcc
	s_ashr_i32 s21, s6, 31
	v_lshlrev_b32_e32 v112, 2, v2
	s_lshl_b64 s[6:7], s[20:21], 13
	v_lshl_or_b32 v2, v9, 9, v11
	v_mov_b32_e32 v3, v65
	v_lshl_add_u64 v[66:67], s[6:7], 0, v[2:3]
	v_or_b32_e32 v2, v10, v6
	v_mov_b32_e32 v3, 0x100
	v_mov_b32_e32 v7, 0x1800
	v_lshl_add_u32 v2, v2, 1, v3
	v_mov_b32_e32 v3, v65
	v_mad_i64_i32 v[70:71], s[10:11], s20, v7, v[2:3]
	v_mov_b32_e32 v2, 0x1a00
	v_add_lshl_u32 v4, v10, v62, 1
	v_mov_b32_e32 v5, v65
	s_mul_hi_i32 s12, s20, 0x1a00
	s_mul_i32 s13, s20, 0x1a00
	v_mad_i64_i32 v[72:73], s[10:11], s20, v2, v[64:65]
	v_lshl_or_b32 v64, v9, 7, v12
	s_mov_b32 s18, s20
	s_ashr_i32 s47, s46, 31
	v_mad_i64_i32 v[68:69], s[8:9], s20, v7, v[4:5]
	v_or_b32_e32 v74, s13, v12
	v_mov_b32_e32 v75, s12
	v_mad_i64_i32 v[76:77], s[12:13], s20, v2, v[64:65]
	v_writelane_b32 v255, s18, 3
	s_lshl_b32 s27, s3, 8
	s_lshl_b64 s[6:7], s[46:47], 13
	s_mul_hi_i32 s9, s46, 0x1800
	s_mul_i32 s8, s46, 0x1800
	s_mul_hi_i32 s11, s46, 0x1a00
	s_mul_i32 s10, s46, 0x1a00
	s_mov_b32 s28, 0x11000000
	s_mov_b64 s[12:13], 0x1e000000
	s_mov_b32 s29, 0x1e000000
	s_mov_b64 s[14:15], 0x2a000000
	s_mov_b32 s30, 0x2a000000
	s_mov_b64 s[16:17], 0x2a000040
	v_mov_b32_e32 v113, 0x358637bd
	v_lshlrev_b32_e32 v64, 2, v62
	v_lshlrev_b32_e32 v78, 2, v6
	v_mov_b32_e32 v79, v65
	v_lshlrev_b32_e32 v80, 2, v8
	v_mov_b32_e32 v81, v65
	v_writelane_b32 v255, s19, 4
	s_mov_b32 s31, s20
	v_mbcnt_lo_u32_b32 v188, -1, 0
	v_mbcnt_hi_u32_b32 v188, -1, v188
	v_readlane_b32 s40, v255, 2
	s_lshl_b32 s40, s40, 14
	v_lshl_add_u32 v254, v188, 7, s40
	v_lshlrev_b32_e32 v188, 4, v188
	v_add_u32_e32 v189, s40, v188
.LBB0_275:
	v_lshl_add_u64 v[6:7], s[96:97], 0, v[72:73]
	v_lshl_add_u64 v[2:3], s[96:97], 0, v[68:69]
	v_add_co_u32_e32 v6, vcc, 0x11000000, v6
	s_mov_b64 s[20:21], s[62:63]
	s_mov_b64 s[18:19], s[76:77]
	s_mov_b32 s64, s31
	s_mov_b32 s65, 0
	s_lshl_b64 s[64:65], s[64:65], 13
	s_add_u32 s64, s64, s96
	s_addc_u32 s65, s65, s97
	s_add_u32 s64, s64, 0x2a000000
	s_addc_u32 s65, s65, 0
	s_add_u32 s66, s64, 0x1000
	s_addc_u32 s67, s65, 0
	v_lshl_add_u64 v[186:187], s[76:77], 0, v[80:81]
	global_load_dwordx4 v[190:193], v[186:187], off
	global_load_dwordx4 v[194:197], v[186:187], off offset:16
	global_load_dwordx4 v[198:201], v[186:187], off offset:32
	global_load_dwordx4 v[202:205], v[186:187], off offset:48
	global_load_dwordx4 v[206:209], v[186:187], off offset:64
	global_load_dwordx4 v[210:213], v[186:187], off offset:80
	global_load_dwordx4 v[214:217], v[186:187], off offset:96
	global_load_dwordx4 v[218:221], v[186:187], off offset:112
	global_load_dwordx4 v[222:225], v[186:187], off offset:128
	global_load_dwordx4 v[226:229], v[186:187], off offset:144
	global_load_dwordx4 v[230:233], v[186:187], off offset:160
	global_load_dwordx4 v[234:237], v[186:187], off offset:176
	global_load_dwordx4 v[238:241], v[186:187], off offset:192
	global_load_dwordx4 v[242:245], v[186:187], off offset:208
	global_load_dwordx4 v[246:249], v[186:187], off offset:224
	global_load_dwordx4 v[250:253], v[186:187], off offset:240
	v_lshl_add_u64 v[4:5], v[2:3], 0, s[12:13]
	v_addc_co_u32_e32 v7, vcc, 0, v7, vcc
	global_load_dwordx4 v[48:51], v[4:5], off offset:32
	global_load_dwordx4 v[52:55], v[4:5], off offset:48
	global_load_dwordx4 v[56:59], v[6:7], off
	global_load_dwordx4 v[86:89], v[4:5], off offset:16
	v_add_co_u32_e32 v84, vcc, 0x1e000000, v2
	v_lshl_add_u64 v[4:5], s[96:97], 0, v[74:75]
	s_nop 0
	v_addc_co_u32_e32 v85, vcc, 0, v3, vcc
	global_load_dwordx4 v[90:93], v[84:85], off
	v_add_co_u32_e32 v44, vcc, s28, v4
	v_lshl_add_u64 v[42:43], s[96:97], 0, v[66:67]
	s_nop 0
	v_addc_co_u32_e32 v45, vcc, 0, v5, vcc
	v_add_co_u32_e32 v82, vcc, s30, v42
	v_lshl_add_u64 v[2:3], s[96:97], 0, v[70:71]
	s_nop 0
	v_addc_co_u32_e32 v83, vcc, 0, v43, vcc
	v_add_co_u32_e32 v100, vcc, s29, v2
	s_and_b32 s33, s26, 0x7ffe0
	s_nop 0
	v_addc_co_u32_e32 v101, vcc, 0, v3, vcc
	global_load_dwordx4 v[34:37], v[100:101], off
	global_load_dwordx4 v[38:41], v[100:101], off offset:64
	s_lshl_b32 s33, s33, 2
	s_add_u32 s34, s22, s33
	v_mov_b32_e32 v8, v62
	s_addc_u32 s35, s23, 0
	s_add_u32 s38, s24, s33
	v_lshl_add_u64 v[46:47], v[42:43], 0, s[14:15]
	s_addc_u32 s39, s25, 0
	global_load_dwordx4 v[30:33], v[6:7], off offset:1024
	global_load_dwordx4 v[26:29], v[44:45], off offset:2048
	global_load_dwordx4 v[18:21], v188, s[64:65] offset:3072
	global_load_dwordx4 v[22:25], v188, s[64:65] offset:2048
	global_load_dwordx4 v[10:13], v8, s[34:35]
	global_load_dwordx4 v[2:5], v8, s[34:35] offset:16
	global_load_dwordx4 v[14:17], v8, s[38:39]
	s_nop 0
	global_load_dwordx4 v[6:9], v8, s[38:39] offset:16
	v_lshl_add_u64 v[42:43], v[42:43], 0, s[16:17]
	v_lshl_add_u64 v[142:143], s[20:21], 0, v[78:79]
	s_waitcnt vmcnt(0)
	v_lshlrev_b32_e32 v148, 16, v49
	v_and_b32_e32 v149, 0xffff0000, v49
	v_and_b32_e32 v49, 0xffff0000, v56
	v_lshlrev_b32_e32 v145, 16, v48
	v_and_b32_e32 v146, 0xffff0000, v48
	v_lshlrev_b32_e32 v48, 16, v56
	v_mul_f32_e32 v49, v49, v49
	v_lshlrev_b32_e32 v150, 16, v50
	v_and_b32_e32 v151, 0xffff0000, v50
	v_lshlrev_b32_e32 v50, 16, v57
	v_fmac_f32_e32 v49, v48, v48
	v_lshlrev_b32_e32 v152, 16, v51
	v_and_b32_e32 v153, 0xffff0000, v51
	v_and_b32_e32 v51, 0xffff0000, v57
	v_fmac_f32_e32 v49, v50, v50
	v_lshlrev_b32_e32 v154, 16, v52
	v_and_b32_e32 v155, 0xffff0000, v52
	v_lshlrev_b32_e32 v52, 16, v58
	v_fmac_f32_e32 v49, v51, v51
	v_lshlrev_b32_e32 v156, 16, v53
	v_and_b32_e32 v157, 0xffff0000, v53
	v_and_b32_e32 v53, 0xffff0000, v58
	v_fmac_f32_e32 v49, v52, v52
	v_lshlrev_b32_e32 v158, 16, v54
	v_and_b32_e32 v159, 0xffff0000, v54
	v_lshlrev_b32_e32 v54, 16, v59
	v_fmac_f32_e32 v49, v53, v53
	v_lshlrev_b32_e32 v160, 16, v55
	v_and_b32_e32 v161, 0xffff0000, v55
	v_and_b32_e32 v55, 0xffff0000, v59
	v_fmac_f32_e32 v49, v54, v54
	v_fmac_f32_e32 v49, v55, v55
	ds_bpermute_b32 v48, v63, v49
	v_lshlrev_b32_e32 v162, 16, v86
	v_and_b32_e32 v163, 0xffff0000, v86
	v_lshlrev_b32_e32 v164, 16, v87
	v_and_b32_e32 v165, 0xffff0000, v87
	s_waitcnt lgkmcnt(0)
	v_add_f32_e32 v48, v49, v48
	ds_bpermute_b32 v49, v108, v48
	v_lshlrev_b32_e32 v166, 16, v88
	v_and_b32_e32 v167, 0xffff0000, v88
	v_lshlrev_b32_e32 v168, 16, v89
	v_and_b32_e32 v169, 0xffff0000, v89
	s_waitcnt lgkmcnt(0)
	v_add_f32_e32 v48, v48, v49
	ds_bpermute_b32 v49, v109, v48
	v_lshlrev_b32_e32 v170, 16, v90
	v_and_b32_e32 v171, 0xffff0000, v90
	v_lshlrev_b32_e32 v172, 16, v91
	v_and_b32_e32 v173, 0xffff0000, v91
	s_waitcnt lgkmcnt(0)
	v_add_f32_e32 v48, v48, v49
	ds_bpermute_b32 v49, v110, v48
	v_lshlrev_b32_e32 v174, 16, v92
	v_and_b32_e32 v175, 0xffff0000, v92
	v_lshlrev_b32_e32 v176, 16, v93
	v_and_b32_e32 v177, 0xffff0000, v93
	s_waitcnt lgkmcnt(0)
	v_add_f32_e32 v48, v48, v49
	ds_bpermute_b32 v49, v111, v48
	v_mul_f32_e32 v52, v171, v171
	v_fmac_f32_e32 v52, v170, v170
	v_fmac_f32_e32 v52, v172, v172
	v_fmac_f32_e32 v52, v173, v173
	s_waitcnt lgkmcnt(0)
	v_add_f32_e32 v54, v48, v49
	v_lshl_add_u64 v[48:49], s[20:21], 0, v[64:65]
	flat_load_dwordx4 v[86:89], v[48:49]
	flat_load_dwordx4 v[90:93], v[48:49] offset:16
	flat_load_dwordx4 v[114:117], v[48:49] offset:32
	flat_load_dwordx4 v[118:121], v[48:49] offset:48
	flat_load_dwordx4 v[122:125], v[48:49] offset:64
	flat_load_dwordx4 v[126:129], v[48:49] offset:80
	flat_load_dwordx4 v[130:133], v[48:49] offset:96
	flat_load_dwordx4 v[134:137], v[48:49] offset:112
	v_fmac_f32_e32 v52, v174, v174
	v_fmac_f32_e32 v52, v175, v175
	v_fmac_f32_e32 v52, v176, v176
	v_fmac_f32_e32 v52, v177, v177
	v_fmac_f32_e32 v52, v162, v162
	v_fmac_f32_e32 v52, v163, v163
	v_fmac_f32_e32 v52, v164, v164
	v_fmac_f32_e32 v52, v165, v165
	v_fmac_f32_e32 v52, v166, v166
	v_fmac_f32_e32 v52, v167, v167
	v_fmac_f32_e32 v52, v168, v168
	v_fmac_f32_e32 v52, v169, v169
	v_fmac_f32_e32 v52, v145, v145
	v_fmac_f32_e32 v52, v146, v146
	v_fmac_f32_e32 v52, v148, v148
	v_fmac_f32_e32 v52, v149, v149
	v_fmac_f32_e32 v52, v150, v150
	v_fmac_f32_e32 v52, v151, v151
	v_fmac_f32_e32 v52, v152, v152
	v_fmac_f32_e32 v52, v153, v153
	v_fmac_f32_e32 v52, v154, v154
	v_fmac_f32_e32 v52, v155, v155
	v_lshlrev_b32_e32 v99, 16, v41
	v_and_b32_e32 v103, 0xffff0000, v41
	v_fmac_f32_e32 v52, v156, v156
	v_lshlrev_b32_e32 v98, 16, v37
	v_and_b32_e32 v102, 0xffff0000, v37
	v_mov_b32_e32 v50, v103
	v_mov_b32_e32 v51, v99
	v_and_b32_e32 v105, 0xffff0000, v40
	v_and_b32_e32 v104, 0xffff0000, v36
	v_fmac_f32_e32 v52, v157, v157
	v_mov_b32_e32 v48, v102
	v_mov_b32_e32 v49, v98
	v_pk_mul_f32 v[50:51], v[50:51], v[50:51]
	v_lshlrev_b32_e32 v97, 16, v40
	v_lshlrev_b32_e32 v96, 16, v36
	v_pk_mul_f32 v[36:37], v[104:105], v[104:105]
	v_lshlrev_b32_e32 v95, 16, v39
	v_lshlrev_b32_e32 v94, 16, v35
	v_fmac_f32_e32 v52, v158, v158
	v_pk_fma_f32 v[48:49], v[48:49], v[48:49], v[50:51]
	v_pk_mul_f32 v[50:51], v[96:97], v[96:97]
	v_add_f32_e32 v40, v36, v37
	v_pk_mul_f32 v[36:37], v[94:95], v[94:95]
	v_and_b32_e32 v107, 0xffff0000, v39
	v_and_b32_e32 v106, 0xffff0000, v35
	v_fmac_f32_e32 v52, v159, v159
	v_add_f32_e32 v41, v50, v51
	v_add_f32_e32 v50, v36, v37
	v_pk_mul_f32 v[36:37], v[106:107], v[106:107]
	v_lshlrev_b32_e32 v139, 16, v38
	v_lshlrev_b32_e32 v138, 16, v34
	v_fmac_f32_e32 v52, v160, v160
	v_add_f32_e32 v39, v36, v37
	v_pk_mul_f32 v[36:37], v[138:139], v[138:139]
	v_fmac_f32_e32 v52, v161, v161
	v_add_f32_e32 v35, v36, v37
	v_and_b32_e32 v141, 0xffff0000, v38
	v_and_b32_e32 v140, 0xffff0000, v34
	v_add_f32_e32 v36, v35, v52
	v_pk_mul_f32 v[34:35], v[140:141], v[140:141]
	ds_bpermute_b32 v55, v112, v54
	v_add_f32_e32 v34, v34, v35
	v_add_f32_e32 v34, v34, v36
	v_add_f32_e32 v34, v50, v34
	v_add_f32_e32 v34, v39, v34
	v_add_f32_e32 v34, v41, v34
	v_add_f32_e32 v34, v40, v34
	v_add_f32_e32 v34, v49, v34
	v_add_f32_e32 v34, v48, v34
	ds_bpermute_b32 v35, v63, v34
	s_waitcnt lgkmcnt(0)
	v_add_f32_e32 v36, v54, v55
	v_fmamk_f32 v36, v36, 0x3b000000, v113
	v_rsq_f32_e32 v144, v36
	global_load_dwordx4 v[58:61], v[44:45], off offset:2112
	global_load_dwordx4 v[50:53], v188, s[64:65] offset:1024
	v_add_f32_e32 v38, v34, v35
	ds_bpermute_b32 v39, v108, v38
	global_load_dwordx4 v[54:57], v188, s[64:65]
	global_load_dwordx4 v[46:49], v188, s[66:67]
	global_load_dwordx4 v[34:37], v188, s[66:67] offset:3072
	s_waitcnt lgkmcnt(0)
	v_add_f32_e32 v38, v38, v39
	v_mul_f32_e32 v38, v144, v38
	v_mul_f32_e32 v38, v144, v38
	v_fmamk_f32 v38, v38, 0x3baaaaab, v113
	v_rsq_f32_e32 v178, v38
	global_load_dwordx4 v[38:41], v188, s[66:67] offset:2048
	s_nop 0
	global_load_dwordx4 v[42:45], v188, s[66:67] offset:1024
	v_mul_f32_e32 v144, v144, v178
	v_mul_f32_e32 v144, 0x3dd53b95, v144
	s_waitcnt vmcnt(0)
	v_mul_f32_e32 v86, v86, v144
	v_mul_f32_e32 v87, v87, v144
	v_mul_f32_e32 v88, v88, v144
	v_mul_f32_e32 v89, v89, v144
	v_mul_f32_e32 v86, v86, v170
	v_mul_f32_e32 v87, v87, v171
	v_mul_f32_e32 v88, v88, v172
	v_mul_f32_e32 v89, v89, v173
	v_mul_f32_e32 v90, v90, v144
	v_mul_f32_e32 v91, v91, v144
	v_mul_f32_e32 v92, v92, v144
	v_mul_f32_e32 v93, v93, v144
	v_mul_f32_e32 v90, v90, v174
	v_mul_f32_e32 v91, v91, v175
	v_mul_f32_e32 v92, v92, v176
	v_mul_f32_e32 v93, v93, v177
	v_mul_f32_e32 v114, v114, v144
	v_mul_f32_e32 v115, v115, v144
	v_mul_f32_e32 v116, v116, v144
	v_mul_f32_e32 v117, v117, v144
	v_mul_f32_e32 v118, v118, v144
	v_mul_f32_e32 v119, v119, v144
	v_mul_f32_e32 v120, v120, v144
	v_mul_f32_e32 v121, v121, v144
	v_cvt_pk_bf16_f32 v86, v86, v87
	v_cvt_pk_bf16_f32 v87, v88, v89
	v_cvt_pk_bf16_f32 v88, v90, v91
	v_cvt_pk_bf16_f32 v89, v92, v93
	v_mul_f32_e32 v114, v114, v162
	v_mul_f32_e32 v115, v115, v163
	v_mul_f32_e32 v116, v116, v164
	v_mul_f32_e32 v117, v117, v165
	v_mul_f32_e32 v118, v118, v166
	v_mul_f32_e32 v119, v119, v167
	v_mul_f32_e32 v120, v120, v168
	v_mul_f32_e32 v121, v121, v169
	v_mul_f32_e32 v122, v122, v144
	v_mul_f32_e32 v123, v123, v144
	v_mul_f32_e32 v124, v124, v144
	v_mul_f32_e32 v125, v125, v144
	v_mul_f32_e32 v126, v126, v144
	v_mul_f32_e32 v127, v127, v144
	v_mul_f32_e32 v128, v128, v144
	v_mul_f32_e32 v129, v129, v144
	global_store_dwordx4 v[84:85], v[86:89], off
	v_mul_f32_e32 v122, v122, v145
	v_mul_f32_e32 v123, v123, v146
	v_cvt_pk_bf16_f32 v86, v114, v115
	v_cvt_pk_bf16_f32 v87, v116, v117
	v_cvt_pk_bf16_f32 v88, v118, v119
	v_cvt_pk_bf16_f32 v89, v120, v121
	v_mul_f32_e32 v124, v124, v148
	v_mul_f32_e32 v125, v125, v149
	v_mul_f32_e32 v126, v126, v150
	v_mul_f32_e32 v127, v127, v151
	v_mul_f32_e32 v128, v128, v152
	v_mul_f32_e32 v129, v129, v153
	v_mul_f32_e32 v130, v130, v144
	v_mul_f32_e32 v131, v131, v144
	v_mul_f32_e32 v132, v132, v144
	v_mul_f32_e32 v133, v133, v144
	v_mul_f32_e32 v134, v134, v144
	v_mul_f32_e32 v135, v135, v144
	v_mul_f32_e32 v136, v136, v144
	v_mul_f32_e32 v137, v137, v144
	global_store_dwordx4 v[84:85], v[86:89], off offset:16
	v_mul_f32_e32 v130, v130, v154
	v_mul_f32_e32 v131, v131, v155
	v_cvt_pk_bf16_f32 v86, v122, v123
	v_cvt_pk_bf16_f32 v87, v124, v125
	v_cvt_pk_bf16_f32 v88, v126, v127
	v_cvt_pk_bf16_f32 v89, v128, v129
	v_mul_f32_e32 v132, v132, v156
	v_mul_f32_e32 v133, v133, v157
	v_mul_f32_e32 v134, v134, v158
	v_mul_f32_e32 v135, v135, v159
	v_mul_f32_e32 v136, v136, v160
	v_mul_f32_e32 v137, v137, v161
	global_store_dwordx4 v[84:85], v[86:89], off offset:32
	v_pk_mul_f32 v[92:93], v[144:145], v[138:139] op_sel_hi:[0,1]
	v_mov_b32_e32 v90, v10
	v_cvt_pk_bf16_f32 v86, v130, v131
	v_cvt_pk_bf16_f32 v87, v132, v133
	v_cvt_pk_bf16_f32 v88, v134, v135
	v_cvt_pk_bf16_f32 v89, v136, v137
	global_store_dwordx4 v[84:85], v[86:89], off offset:48
	flat_load_dwordx4 v[114:117], v[142:143] offset:512
	flat_load_dwordx4 v[118:121], v[142:143] offset:640
	flat_load_dwordx4 v[122:125], v[142:143] offset:528
	flat_load_dwordx4 v[126:129], v[142:143] offset:656
	v_mov_b32_e32 v91, v14
	v_pk_mul_f32 v[94:95], v[144:145], v[94:95] op_sel_hi:[0,1]
	v_mov_b32_e32 v88, v12
	v_mov_b32_e32 v89, v16
	v_pk_mul_f32 v[106:107], v[144:145], v[106:107] op_sel_hi:[0,1]
	v_pk_mul_f32 v[96:97], v[144:145], v[96:97] op_sel_hi:[0,1]
	v_mov_b32_e32 v86, v2
	v_mov_b32_e32 v87, v6
	v_pk_mul_f32 v[104:105], v[144:145], v[104:105] op_sel_hi:[0,1]
	v_pk_mul_f32 v[98:99], v[144:145], v[98:99] op_sel_hi:[0,1]
	v_mov_b32_e32 v84, v4
	v_mov_b32_e32 v85, v8
	v_pk_mul_f32 v[102:103], v[144:145], v[102:103] op_sel_hi:[0,1]
	s_waitcnt vmcnt(0) lgkmcnt(0)
	ds_write_b128 v189, v[54:57]
	ds_write_b128 v189, v[50:53] offset:1024
	ds_write_b128 v189, v[22:25] offset:2048
	ds_write_b128 v189, v[18:21] offset:3072
	ds_write_b128 v189, v[46:49] offset:4096
	ds_write_b128 v189, v[42:45] offset:5120
	ds_write_b128 v189, v[38:41] offset:6144
	ds_write_b128 v189, v[34:37] offset:7168
	s_waitcnt lgkmcnt(0)
	ds_read_b128 v[54:57], v254
	ds_read_b128 v[50:53], v254 offset:16
	ds_read_b128 v[22:25], v254 offset:32
	ds_read_b128 v[18:21], v254 offset:48
	ds_read_b128 v[46:49], v254 offset:64
	ds_read_b128 v[42:45], v254 offset:80
	ds_read_b128 v[38:41], v254 offset:96
	ds_read_b128 v[34:37], v254 offset:112
	s_waitcnt lgkmcnt(0)
	v_mov_b32_e32 v130, v114
	v_mov_b32_e32 v131, v118
	v_pk_mul_f32 v[130:131], v[92:93], v[130:131]
	v_mov_b32_e32 v118, v115
	v_pk_mul_f32 v[92:93], v[90:91], v[130:131]
	s_nop 0
	v_sub_f32_e32 v132, v92, v93
	v_mov_b32_e32 v92, v14
	v_mov_b32_e32 v93, v10
	v_pk_mul_f32 v[130:131], v[92:93], v[130:131]
	v_mov_b32_e32 v14, v11
	v_add_f32_e32 v133, v130, v131
	v_pk_mul_f32 v[130:131], v[144:145], v[140:141] op_sel_hi:[0,1]
	v_pk_mul_f32 v[114:115], v[130:131], v[118:119]
	v_mov_b32_e32 v10, v15
	v_pk_mul_f32 v[118:119], v[14:15], v[114:115]
	v_pk_mul_f32 v[114:115], v[10:11], v[114:115]
	v_sub_f32_e32 v118, v118, v119
	v_add_f32_e32 v119, v114, v115
	v_mov_b32_e32 v114, v116
	v_mov_b32_e32 v115, v120
	v_pk_mul_f32 v[114:115], v[94:95], v[114:115]
	v_mov_b32_e32 v120, v117
	v_pk_mul_f32 v[94:95], v[88:89], v[114:115]
	v_pk_mul_f32 v[106:107], v[106:107], v[120:121]
	v_sub_f32_e32 v116, v94, v95
	v_mov_b32_e32 v94, v16
	v_mov_b32_e32 v95, v12
	v_pk_mul_f32 v[114:115], v[94:95], v[114:115]
	v_mov_b32_e32 v16, v13
	v_mov_b32_e32 v12, v17
	v_add_f32_e32 v130, v114, v115
	v_pk_mul_f32 v[114:115], v[16:17], v[106:107]
	v_pk_mul_f32 v[106:107], v[12:13], v[106:107]
	v_sub_f32_e32 v114, v114, v115
	v_add_f32_e32 v115, v106, v107
	v_mov_b32_e32 v106, v122
	v_mov_b32_e32 v107, v126
	v_pk_mul_f32 v[106:107], v[96:97], v[106:107]
	v_mov_b32_e32 v126, v123
	v_pk_mul_f32 v[96:97], v[86:87], v[106:107]
	v_pk_mul_f32 v[104:105], v[104:105], v[126:127]
	v_sub_f32_e32 v117, v96, v97
	v_mov_b32_e32 v96, v6
	v_mov_b32_e32 v97, v2
	v_pk_mul_f32 v[106:107], v[96:97], v[106:107]
	v_mov_b32_e32 v6, v3
	v_mov_b32_e32 v2, v7
	v_add_f32_e32 v120, v106, v107
	v_pk_mul_f32 v[106:107], v[6:7], v[104:105]
	v_pk_mul_f32 v[104:105], v[2:3], v[104:105]
	v_sub_f32_e32 v106, v106, v107
	v_add_f32_e32 v107, v104, v105
	v_mov_b32_e32 v104, v124
	v_mov_b32_e32 v105, v128
	v_pk_mul_f32 v[104:105], v[98:99], v[104:105]
	v_mov_b32_e32 v128, v125
	v_pk_mul_f32 v[98:99], v[84:85], v[104:105]
	v_pk_mul_f32 v[102:103], v[102:103], v[128:129]
	v_sub_f32_e32 v121, v98, v99
	v_mov_b32_e32 v98, v8
	v_mov_b32_e32 v99, v4
	v_pk_mul_f32 v[104:105], v[98:99], v[104:105]
	v_mov_b32_e32 v8, v5
	v_add_f32_e32 v122, v104, v105
	v_pk_mul_f32 v[104:105], v[8:9], v[102:103]
	v_mov_b32_e32 v4, v9
	v_sub_f32_e32 v105, v104, v105
	v_pk_mul_f32 v[102:103], v[4:5], v[102:103]
	s_nop 0
	v_add_f32_e32 v123, v102, v103
	v_cvt_pk_bf16_f32 v102, v132, v118
	v_cvt_pk_bf16_f32 v103, v116, v114
	v_cvt_pk_bf16_f32 v104, v117, v106
	v_cvt_pk_bf16_f32 v105, v121, v105
	global_store_dwordx4 v[100:101], v[102:105], off
	s_nop 1
	v_cvt_pk_bf16_f32 v102, v133, v119
	v_cvt_pk_bf16_f32 v103, v130, v115
	v_cvt_pk_bf16_f32 v104, v120, v107
	v_cvt_pk_bf16_f32 v105, v122, v123
	global_store_dwordx4 v[100:101], v[102:105], off offset:64
	v_and_b32_e32 v146, 0xffff0000, v54
	v_lshlrev_b32_e32 v148, 16, v54
	v_mul_f32_e32 v185, v146, v146
	v_lshlrev_b32_e32 v145, 16, v55
	v_fmac_f32_e32 v185, v148, v148
	v_and_b32_e32 v144, 0xffff0000, v55
	v_fmac_f32_e32 v185, v145, v145
	v_lshlrev_b32_e32 v152, 16, v56
	v_fmac_f32_e32 v185, v144, v144
	v_and_b32_e32 v151, 0xffff0000, v56
	v_fmac_f32_e32 v185, v152, v152
	v_lshlrev_b32_e32 v150, 16, v57
	v_fmac_f32_e32 v185, v151, v151
	v_and_b32_e32 v149, 0xffff0000, v57
	v_fmac_f32_e32 v185, v150, v150
	v_lshlrev_b32_e32 v139, 16, v50
	v_fmac_f32_e32 v185, v149, v149
	v_and_b32_e32 v158, 0xffff0000, v30
	v_lshlrev_b32_e32 v156, 16, v31
	v_and_b32_e32 v155, 0xffff0000, v31
	v_lshlrev_b32_e32 v154, 16, v32
	v_and_b32_e32 v153, 0xffff0000, v32
	v_and_b32_e32 v106, 0xffff0000, v33
	v_lshlrev_b32_e32 v107, 16, v33
	v_and_b32_e32 v31, 0xffff0000, v58
	v_lshlrev_b32_e32 v33, 16, v59
	v_lshlrev_b32_e32 v32, 16, v58
	v_and_b32_e32 v138, 0xffff0000, v50
	v_fmac_f32_e32 v185, v139, v139
	v_lshlrev_b32_e32 v157, 16, v30
	v_and_b32_e32 v30, 0xffff0000, v26
	v_lshlrev_b32_e32 v101, 16, v27
	v_lshlrev_b32_e32 v100, 16, v26
	v_lshlrev_b32_e32 v103, 16, v28
	v_and_b32_e32 v102, 0xffff0000, v27
	v_lshlrev_b32_e32 v27, 16, v60
	v_lshlrev_b32_e32 v105, 16, v29
	v_and_b32_e32 v104, 0xffff0000, v28
	v_and_b32_e32 v58, 0xffff0000, v60
	v_and_b32_e32 v60, 0xffff0000, v29
	v_lshlrev_b32_e32 v137, 16, v51
	v_lshlrev_b32_e32 v115, 16, v46
	v_and_b32_e32 v114, 0xffff0000, v46
	v_lshlrev_b32_e32 v57, 16, v47
	v_and_b32_e32 v56, 0xffff0000, v47
	v_lshlrev_b32_e32 v47, 16, v40
	v_and_b32_e32 v46, 0xffff0000, v40
	v_and_b32_e32 v28, 0xffff0000, v41
	v_lshlrev_b32_e32 v29, 16, v41
	v_mul_f32_e32 v184, v158, v158
	v_pk_mul_f32 v[40:41], v[106:107], v[106:107]
	v_mul_f32_e32 v106, v31, v31
	v_pk_mul_f32 v[166:167], v[32:33], v[32:33]
	v_fmac_f32_e32 v185, v138, v138
	v_and_b32_e32 v26, 0xffff0000, v59
	v_and_b32_e32 v136, 0xffff0000, v51
	v_lshlrev_b32_e32 v123, 16, v18
	v_and_b32_e32 v122, 0xffff0000, v18
	v_lshlrev_b32_e32 v121, 16, v19
	v_and_b32_e32 v120, 0xffff0000, v19
	v_lshlrev_b32_e32 v127, 16, v20
	v_and_b32_e32 v126, 0xffff0000, v20
	v_lshlrev_b32_e32 v125, 16, v21
	v_and_b32_e32 v124, 0xffff0000, v21
	v_and_b32_e32 v18, 0xffff0000, v34
	v_lshlrev_b32_e32 v19, 16, v34
	v_and_b32_e32 v20, 0xffff0000, v35
	v_lshlrev_b32_e32 v21, 16, v35
	v_lshl_add_u64 v[34:35], s[18:19], 0, v[80:81]
	v_fmac_f32_e32 v184, v157, v157
	v_pk_fma_f32 v[106:107], v[30:31], v[30:31], v[106:107] op_sel_hi:[1,1,0]
	v_pk_fma_f32 v[166:167], v[100:101], v[100:101], v[166:167]
	v_fmac_f32_e32 v185, v137, v137
	v_lshlrev_b32_e32 v143, 16, v52
	v_pk_mul_f32 v[168:169], v[26:27], v[26:27]
	v_mov_b32_e32 v158, v190
	v_mov_b32_e32 v159, v191
	v_mov_b32_e32 v160, v192
	v_mov_b32_e32 v161, v193
	v_mov_b32_e32 v162, v194
	v_mov_b32_e32 v163, v195
	v_mov_b32_e32 v164, v196
	v_mov_b32_e32 v165, v197
	v_fmac_f32_e32 v184, v156, v156
	v_pk_add_f32 v[106:107], v[166:167], v[106:107]
	v_fmac_f32_e32 v185, v136, v136
	v_lshlrev_b32_e32 v59, 16, v61
	v_and_b32_e32 v142, 0xffff0000, v52
	v_pk_fma_f32 v[168:169], v[102:103], v[102:103], v[168:169]
	v_fmac_f32_e32 v184, v155, v155
	v_pk_add_f32 v[106:107], v[166:167], v[106:107] op_sel:[1,0] op_sel_hi:[0,1]
	v_fmac_f32_e32 v185, v143, v143
	v_lshlrev_b32_e32 v141, 16, v53
	v_pk_mul_f32 v[170:171], v[58:59], v[58:59]
	v_fmac_f32_e32 v184, v154, v154
	v_pk_add_f32 v[106:107], v[168:169], v[106:107]
	v_fmac_f32_e32 v185, v142, v142
	v_and_b32_e32 v140, 0xffff0000, v53
	v_pk_fma_f32 v[170:171], v[104:105], v[104:105], v[170:171]
	v_fmac_f32_e32 v184, v153, v153
	v_pk_add_f32 v[106:107], v[168:169], v[106:107] op_sel:[1,0] op_sel_hi:[0,1]
	v_fmac_f32_e32 v185, v141, v141
	v_lshlrev_b32_e32 v131, 16, v22
	v_add_f32_e32 v41, v41, v184
	v_pk_add_f32 v[106:107], v[170:171], v[106:107]
	v_fmac_f32_e32 v185, v140, v140
	v_and_b32_e32 v130, 0xffff0000, v22
	v_add_f32_e32 v153, v40, v41
	v_pk_add_f32 v[40:41], v[170:171], v[106:107] op_sel:[1,0] op_sel_hi:[0,1]
	v_fmac_f32_e32 v185, v131, v131
	v_lshlrev_b32_e32 v129, 16, v23
	ds_bpermute_b32 v41, v63, v153
	v_fmac_f32_e32 v185, v130, v130
	v_and_b32_e32 v128, 0xffff0000, v23
	v_fmac_f32_e32 v185, v129, v129
	v_lshlrev_b32_e32 v135, 16, v24
	v_fmac_f32_e32 v185, v128, v128
	v_and_b32_e32 v134, 0xffff0000, v24
	v_fmac_f32_e32 v185, v135, v135
	v_lshlrev_b32_e32 v133, 16, v25
	v_fmac_f32_e32 v185, v134, v134
	v_and_b32_e32 v132, 0xffff0000, v25
	s_waitcnt lgkmcnt(0)
	v_add_f32_e32 v41, v153, v41
	v_fmac_f32_e32 v185, v133, v133
	ds_bpermute_b32 v106, v108, v41
	v_fmac_f32_e32 v185, v132, v132
	v_fmac_f32_e32 v185, v123, v123
	v_fmac_f32_e32 v185, v122, v122
	v_fmac_f32_e32 v185, v121, v121
	v_fmac_f32_e32 v185, v120, v120
	s_waitcnt lgkmcnt(0)
	v_add_f32_e32 v41, v41, v106
	v_fmac_f32_e32 v185, v127, v127
	ds_bpermute_b32 v106, v109, v41
	v_fmac_f32_e32 v185, v126, v126
	v_fmac_f32_e32 v185, v125, v125
	v_fmac_f32_e32 v185, v124, v124
	v_fmac_f32_e32 v185, v115, v115
	v_fmac_f32_e32 v185, v114, v114
	s_waitcnt lgkmcnt(0)
	v_add_f32_e32 v41, v41, v106
	v_fmac_f32_e32 v185, v57, v57
	v_lshlrev_b32_e32 v119, 16, v48
	ds_bpermute_b32 v106, v110, v41
	v_fmac_f32_e32 v185, v56, v56
	v_and_b32_e32 v118, 0xffff0000, v48
	v_fmac_f32_e32 v185, v119, v119
	v_lshlrev_b32_e32 v117, 16, v49
	v_fmac_f32_e32 v185, v118, v118
	v_and_b32_e32 v116, 0xffff0000, v49
	v_fmac_f32_e32 v185, v117, v117
	v_lshlrev_b32_e32 v51, 16, v42
	v_fmac_f32_e32 v185, v116, v116
	v_and_b32_e32 v50, 0xffff0000, v42
	s_waitcnt lgkmcnt(0)
	v_add_f32_e32 v41, v41, v106
	v_fmac_f32_e32 v185, v51, v51
	v_lshlrev_b32_e32 v49, 16, v43
	ds_bpermute_b32 v106, v111, v41
	v_fmac_f32_e32 v185, v50, v50
	v_and_b32_e32 v48, 0xffff0000, v43
	v_fmac_f32_e32 v185, v49, v49
	v_lshlrev_b32_e32 v55, 16, v44
	v_fmac_f32_e32 v185, v48, v48
	v_and_b32_e32 v54, 0xffff0000, v44
	v_fmac_f32_e32 v185, v55, v55
	v_lshlrev_b32_e32 v53, 16, v45
	v_fmac_f32_e32 v185, v54, v54
	v_and_b32_e32 v52, 0xffff0000, v45
	s_waitcnt lgkmcnt(0)
	v_add_f32_e32 v41, v41, v106
	v_fmac_f32_e32 v185, v53, v53
	v_lshlrev_b32_e32 v45, 16, v38
	ds_bpermute_b32 v106, v112, v41
	v_fmac_f32_e32 v185, v52, v52
	v_and_b32_e32 v44, 0xffff0000, v38
	v_fmac_f32_e32 v185, v45, v45
	v_lshlrev_b32_e32 v43, 16, v39
	v_fmac_f32_e32 v185, v44, v44
	v_and_b32_e32 v42, 0xffff0000, v39
	v_fmac_f32_e32 v185, v43, v43
	v_fmac_f32_e32 v185, v42, v42
	s_waitcnt lgkmcnt(0)
	v_add_f32_e32 v41, v41, v106
	v_fmac_f32_e32 v185, v47, v47
	v_pk_mul_f32 v[172:173], v[28:29], v[28:29]
	v_fmamk_f32 v41, v41, 0x3b000000, v113
	v_fmac_f32_e32 v185, v46, v46
	v_rsq_f32_e32 v153, v41
	v_add_f32_e32 v41, v173, v185
	v_pk_mul_f32 v[174:175], v[18:19], v[18:19]
	v_add_f32_e32 v41, v172, v41
	v_add_f32_e32 v41, v175, v41
	v_pk_mul_f32 v[176:177], v[20:21], v[20:21]
	v_add_f32_e32 v41, v174, v41
	v_and_b32_e32 v22, 0xffff0000, v36
	v_lshlrev_b32_e32 v23, 16, v36
	v_add_f32_e32 v41, v177, v41
	v_pk_mul_f32 v[178:179], v[22:23], v[22:23]
	v_add_f32_e32 v41, v176, v41
	v_and_b32_e32 v24, 0xffff0000, v37
	v_lshlrev_b32_e32 v25, 16, v37
	v_add_f32_e32 v41, v179, v41
	v_and_b32_e32 v61, 0xffff0000, v61
	v_pk_mul_f32 v[180:181], v[24:25], v[24:25]
	v_add_f32_e32 v41, v178, v41
	v_mul_f32_e32 v182, v61, v61
	v_add_f32_e32 v41, v181, v41
	v_pk_fma_f32 v[182:183], v[60:61], v[60:61], v[182:183] op_sel_hi:[1,1,0]
	v_add_f32_e32 v41, v180, v41
	v_cndmask_b32_e64 v183, 0, v41, s[0:1]
	ds_bpermute_b32 v106, v63, v183
	s_waitcnt vmcnt(0)
	v_cndmask_b32_e64 v155, v159, 1.0, s[4:5]
	v_cndmask_b32_e64 v156, v158, 1.0, s[4:5]
	v_cndmask_b32_e64 v159, v163, 1.0, s[4:5]
	v_cndmask_b32_e64 v154, v160, 1.0, s[4:5]
	s_waitcnt lgkmcnt(0)
	v_mov_b32_e32 v41, v106
	v_pk_add_f32 v[40:41], v[182:183], v[40:41]
	ds_bpermute_b32 v106, v63, v40
	ds_bpermute_b32 v107, v108, v41
	v_cndmask_b32_e64 v157, v165, 1.0, s[4:5]
	v_cndmask_b32_e64 v158, v164, 1.0, s[4:5]
	v_cndmask_b32_e64 v160, v162, 1.0, s[4:5]
	v_lshl_add_u64 v[36:37], s[18:19], 0, v[78:79]
	s_waitcnt lgkmcnt(0)
	v_pk_add_f32 v[40:41], v[40:41], v[106:107]
	ds_bpermute_b32 v106, v108, v40
	v_mul_f32_e32 v41, v41, v153
	v_cndmask_b32_e64 v107, v161, 1.0, s[4:5]
	v_lshl_add_u64 v[38:39], s[96:97], 0, v[76:77]
	s_add_i32 s31, s31, s46
	s_waitcnt lgkmcnt(0)
	v_add_f32_e32 v40, v40, v106
	v_fmac_f32_e32 v40, v153, v41
	v_fmamk_f32 v40, v40, 0x3baaaaab, v113
	v_rsq_f32_e32 v40, v40
	s_add_i32 s26, s26, s27
	v_add_co_u32_e32 v38, vcc, s28, v38
	v_mul_f32_e32 v41, v153, v40
	v_cndmask_b32_e64 v41, v153, v41, s[0:1]
	v_mul_f32_e32 v106, v156, v41
	v_mul_f32_e32 v156, v159, v41
	v_mul_f32_e32 v153, v160, v41
	v_mul_f32_e32 v155, v155, v41
	v_mul_f32_e32 v154, v154, v41
	v_mul_f32_e32 v158, v158, v41
	v_mul_f32_e32 v107, v107, v41
	v_mul_f32_e32 v157, v157, v41
	v_mul_f32_e32 v151, v156, v151
	v_mul_f32_e32 v106, v106, v148
	v_mul_f32_e32 v152, v153, v152
	v_mul_f32_e32 v146, v155, v146
	v_mul_f32_e32 v145, v154, v145
	v_mul_f32_e32 v153, v158, v150
	v_mul_f32_e32 v107, v107, v144
	v_mul_f32_e32 v144, v157, v149
	v_cvt_pk_bf16_f32 v148, v106, v146
	v_cvt_pk_bf16_f32 v149, v145, v107
	v_cvt_pk_bf16_f32 v150, v152, v151
	v_cvt_pk_bf16_f32 v151, v153, v144
	ds_write_b128 v254, v[148:151]
	s_nop 1
	v_mov_b32_e32 v148, v198
	v_mov_b32_e32 v149, v199
	v_mov_b32_e32 v150, v200
	v_mov_b32_e32 v151, v201
	s_nop 0
	v_mov_b32_e32 v152, v202
	v_mov_b32_e32 v153, v203
	v_mov_b32_e32 v154, v204
	v_mov_b32_e32 v155, v205
	v_lshl_add_u64 v[66:67], v[66:67], 0, s[6:7]
	v_lshl_add_u64 v[68:69], v[68:69], 0, s[8:9]
	v_lshl_add_u64 v[70:71], v[70:71], 0, s[8:9]
	v_lshl_add_u64 v[72:73], v[72:73], 0, s[10:11]
	v_lshl_add_u64 v[74:75], v[74:75], 0, s[10:11]
	v_lshl_add_u64 v[76:77], v[76:77], 0, s[10:11]
	v_addc_co_u32_e32 v39, vcc, 0, v39, vcc
	s_cmp_lt_i32 s31, 0x8000
	s_waitcnt lgkmcnt(0)
	v_cndmask_b32_e64 v144, v149, 1.0, s[4:5]
	v_cndmask_b32_e64 v145, v148, 1.0, s[4:5]
	v_cndmask_b32_e64 v106, v151, 1.0, s[4:5]
	v_cndmask_b32_e64 v107, v150, 1.0, s[4:5]
	v_cndmask_b32_e64 v146, v155, 1.0, s[4:5]
	v_cndmask_b32_e64 v148, v154, 1.0, s[4:5]
	v_cndmask_b32_e64 v149, v153, 1.0, s[4:5]
	v_cndmask_b32_e64 v150, v152, 1.0, s[4:5]
	v_mul_f32_e32 v145, v145, v41
	v_mul_f32_e32 v144, v144, v41
	v_mul_f32_e32 v150, v41, v150
	v_mul_f32_e32 v149, v41, v149
	v_mul_f32_e32 v107, v107, v41
	v_mul_f32_e32 v148, v41, v148
	v_mul_f32_e32 v106, v106, v41
	v_mul_f32_e32 v146, v41, v146
	v_mul_f32_e32 v139, v145, v139
	v_mul_f32_e32 v138, v144, v138
	v_mul_f32_e32 v143, v150, v143
	v_mul_f32_e32 v142, v149, v142
	v_mul_f32_e32 v107, v107, v137
	v_mul_f32_e32 v141, v148, v141
	v_mul_f32_e32 v106, v106, v136
	v_mul_f32_e32 v140, v146, v140
	v_cvt_pk_bf16_f32 v136, v139, v138
	v_cvt_pk_bf16_f32 v137, v107, v106
	v_cvt_pk_bf16_f32 v138, v143, v142
	v_cvt_pk_bf16_f32 v139, v141, v140
	ds_write_b128 v254, v[136:139] offset:16
	s_nop 1
	v_mov_b32_e32 v136, v206
	v_mov_b32_e32 v137, v207
	v_mov_b32_e32 v138, v208
	v_mov_b32_e32 v139, v209
	s_nop 0
	v_mov_b32_e32 v140, v210
	v_mov_b32_e32 v141, v211
	v_mov_b32_e32 v142, v212
	v_mov_b32_e32 v143, v213
	s_waitcnt lgkmcnt(0)
	v_cndmask_b32_e64 v137, v137, 1.0, s[4:5]
	v_cndmask_b32_e64 v136, v136, 1.0, s[4:5]
	v_cndmask_b32_e64 v106, v139, 1.0, s[4:5]
	v_cndmask_b32_e64 v107, v138, 1.0, s[4:5]
	v_cndmask_b32_e64 v138, v143, 1.0, s[4:5]
	v_cndmask_b32_e64 v139, v142, 1.0, s[4:5]
	v_cndmask_b32_e64 v141, v141, 1.0, s[4:5]
	v_cndmask_b32_e64 v140, v140, 1.0, s[4:5]
	v_mul_f32_e32 v136, v41, v136
	v_mul_f32_e32 v137, v41, v137
	v_mul_f32_e32 v140, v41, v140
	v_mul_f32_e32 v141, v41, v141
	v_mul_f32_e32 v107, v41, v107
	v_mul_f32_e32 v139, v41, v139
	v_mul_f32_e32 v106, v41, v106
	v_mul_f32_e32 v138, v41, v138
	v_mul_f32_e32 v131, v136, v131
	v_mul_f32_e32 v130, v137, v130
	v_mul_f32_e32 v135, v140, v135
	v_mul_f32_e32 v134, v141, v134
	v_mul_f32_e32 v107, v107, v129
	v_mul_f32_e32 v133, v139, v133
	v_mul_f32_e32 v106, v106, v128
	v_mul_f32_e32 v132, v138, v132
	v_cvt_pk_bf16_f32 v128, v131, v130
	v_cvt_pk_bf16_f32 v129, v107, v106
	v_cvt_pk_bf16_f32 v130, v135, v134
	v_cvt_pk_bf16_f32 v131, v133, v132
	ds_write_b128 v254, v[128:131] offset:32
	s_nop 1
	v_mov_b32_e32 v128, v214
	v_mov_b32_e32 v129, v215
	v_mov_b32_e32 v130, v216
	v_mov_b32_e32 v131, v217
	s_nop 0
	v_mov_b32_e32 v132, v218
	v_mov_b32_e32 v133, v219
	v_mov_b32_e32 v134, v220
	v_mov_b32_e32 v135, v221
	s_waitcnt lgkmcnt(0)
	v_cndmask_b32_e64 v129, v129, 1.0, s[4:5]
	v_cndmask_b32_e64 v128, v128, 1.0, s[4:5]
	v_cndmask_b32_e64 v106, v131, 1.0, s[4:5]
	v_cndmask_b32_e64 v107, v130, 1.0, s[4:5]
	v_cndmask_b32_e64 v130, v135, 1.0, s[4:5]
	v_cndmask_b32_e64 v131, v134, 1.0, s[4:5]
	v_cndmask_b32_e64 v133, v133, 1.0, s[4:5]
	v_cndmask_b32_e64 v132, v132, 1.0, s[4:5]
	v_mul_f32_e32 v128, v41, v128
	v_mul_f32_e32 v129, v41, v129
	v_mul_f32_e32 v132, v41, v132
	v_mul_f32_e32 v133, v41, v133
	v_mul_f32_e32 v107, v41, v107
	v_mul_f32_e32 v131, v41, v131
	v_mul_f32_e32 v106, v41, v106
	v_mul_f32_e32 v130, v41, v130
	v_mul_f32_e32 v123, v128, v123
	v_mul_f32_e32 v122, v129, v122
	v_mul_f32_e32 v127, v132, v127
	v_mul_f32_e32 v126, v133, v126
	v_mul_f32_e32 v107, v107, v121
	v_mul_f32_e32 v125, v131, v125
	v_mul_f32_e32 v106, v106, v120
	v_mul_f32_e32 v124, v130, v124
	v_cvt_pk_bf16_f32 v120, v123, v122
	v_cvt_pk_bf16_f32 v121, v107, v106
	v_cvt_pk_bf16_f32 v122, v127, v126
	v_cvt_pk_bf16_f32 v123, v125, v124
	ds_write_b128 v254, v[120:123] offset:48
	s_nop 1
	v_mov_b32_e32 v120, v222
	v_mov_b32_e32 v121, v223
	v_mov_b32_e32 v122, v224
	v_mov_b32_e32 v123, v225
	s_nop 0
	v_mov_b32_e32 v124, v226
	v_mov_b32_e32 v125, v227
	v_mov_b32_e32 v126, v228
	v_mov_b32_e32 v127, v229
	s_waitcnt lgkmcnt(0)
	v_cndmask_b32_e64 v121, v121, 1.0, s[4:5]
	v_cndmask_b32_e64 v120, v120, 1.0, s[4:5]
	v_cndmask_b32_e64 v106, v123, 1.0, s[4:5]
	v_cndmask_b32_e64 v107, v122, 1.0, s[4:5]
	v_cndmask_b32_e64 v122, v127, 1.0, s[4:5]
	v_cndmask_b32_e64 v123, v126, 1.0, s[4:5]
	v_cndmask_b32_e64 v125, v125, 1.0, s[4:5]
	v_cndmask_b32_e64 v124, v124, 1.0, s[4:5]
	v_mul_f32_e32 v120, v41, v120
	v_mul_f32_e32 v121, v41, v121
	v_mul_f32_e32 v124, v41, v124
	v_mul_f32_e32 v125, v41, v125
	v_mul_f32_e32 v107, v41, v107
	v_mul_f32_e32 v123, v41, v123
	v_mul_f32_e32 v106, v41, v106
	v_mul_f32_e32 v122, v41, v122
	v_mul_f32_e32 v115, v120, v115
	v_mul_f32_e32 v114, v121, v114
	v_mul_f32_e32 v119, v124, v119
	v_mul_f32_e32 v118, v125, v118
	v_mul_f32_e32 v57, v107, v57
	v_mul_f32_e32 v107, v123, v117
	v_mul_f32_e32 v56, v106, v56
	v_mul_f32_e32 v106, v122, v116
	v_cvt_pk_bf16_f32 v114, v115, v114
	v_cvt_pk_bf16_f32 v115, v57, v56
	v_cvt_pk_bf16_f32 v116, v119, v118
	v_cvt_pk_bf16_f32 v117, v107, v106
	ds_write_b128 v254, v[114:117] offset:64
	s_nop 1
	v_mov_b32_e32 v114, v230
	v_mov_b32_e32 v115, v231
	v_mov_b32_e32 v116, v232
	v_mov_b32_e32 v117, v233
	s_nop 0
	v_mov_b32_e32 v118, v234
	v_mov_b32_e32 v119, v235
	v_mov_b32_e32 v120, v236
	v_mov_b32_e32 v121, v237
	s_waitcnt lgkmcnt(0)
	v_cndmask_b32_e64 v57, v116, 1.0, s[4:5]
	v_cndmask_b32_e64 v106, v115, 1.0, s[4:5]
	v_cndmask_b32_e64 v107, v114, 1.0, s[4:5]
	v_cndmask_b32_e64 v56, v117, 1.0, s[4:5]
	v_cndmask_b32_e64 v114, v121, 1.0, s[4:5]
	v_cndmask_b32_e64 v115, v120, 1.0, s[4:5]
	v_cndmask_b32_e64 v116, v119, 1.0, s[4:5]
	v_cndmask_b32_e64 v117, v118, 1.0, s[4:5]
	v_mul_f32_e32 v107, v41, v107
	v_mul_f32_e32 v106, v41, v106
	v_mul_f32_e32 v57, v41, v57
	v_mul_f32_e32 v117, v41, v117
	v_mul_f32_e32 v116, v41, v116
	v_mul_f32_e32 v115, v41, v115
	v_mul_f32_e32 v56, v41, v56
	v_mul_f32_e32 v114, v41, v114
	v_mul_f32_e32 v51, v107, v51
	v_mul_f32_e32 v50, v106, v50
	v_mul_f32_e32 v49, v57, v49
	v_mul_f32_e32 v55, v117, v55
	v_mul_f32_e32 v54, v116, v54
	v_mul_f32_e32 v53, v115, v53
	v_mul_f32_e32 v56, v56, v48
	v_mul_f32_e32 v52, v114, v52
	v_cvt_pk_bf16_f32 v48, v51, v50
	v_cvt_pk_bf16_f32 v49, v49, v56
	v_cvt_pk_bf16_f32 v50, v55, v54
	v_cvt_pk_bf16_f32 v51, v53, v52
	ds_write_b128 v254, v[48:51] offset:80
	s_nop 1
	v_mov_b32_e32 v48, v238
	v_mov_b32_e32 v49, v239
	v_mov_b32_e32 v50, v240
	v_mov_b32_e32 v51, v241
	s_nop 0
	v_mov_b32_e32 v52, v242
	v_mov_b32_e32 v53, v243
	v_mov_b32_e32 v54, v244
	v_mov_b32_e32 v55, v245
	s_waitcnt lgkmcnt(0)
	v_cndmask_b32_e64 v50, v50, 1.0, s[4:5]
	v_cndmask_b32_e64 v49, v49, 1.0, s[4:5]
	v_cndmask_b32_e64 v48, v48, 1.0, s[4:5]
	v_cndmask_b32_e64 v51, v51, 1.0, s[4:5]
	v_cndmask_b32_e64 v55, v55, 1.0, s[4:5]
	v_cndmask_b32_e64 v54, v54, 1.0, s[4:5]
	v_cndmask_b32_e64 v53, v53, 1.0, s[4:5]
	v_cndmask_b32_e64 v52, v52, 1.0, s[4:5]
	v_mul_f32_e32 v48, v41, v48
	v_mul_f32_e32 v49, v41, v49
	v_mul_f32_e32 v50, v41, v50
	v_mul_f32_e32 v52, v41, v52
	v_mul_f32_e32 v53, v41, v53
	v_mul_f32_e32 v54, v41, v54
	v_mul_f32_e32 v51, v41, v51
	v_mul_f32_e32 v55, v41, v55
	v_mul_f32_e32 v45, v48, v45
	v_mul_f32_e32 v44, v49, v44
	v_mul_f32_e32 v43, v50, v43
	v_mul_f32_e32 v47, v52, v47
	v_mul_f32_e32 v46, v53, v46
	v_mul_f32_e32 v29, v54, v29
	v_mul_f32_e32 v48, v51, v42
	v_mul_f32_e32 v28, v55, v28
	v_cvt_pk_bf16_f32 v42, v45, v44
	v_cvt_pk_bf16_f32 v43, v43, v48
	v_cvt_pk_bf16_f32 v44, v47, v46
	v_cvt_pk_bf16_f32 v45, v29, v28
	ds_write_b128 v254, v[42:45] offset:96
	s_nop 1
	v_mov_b32_e32 v42, v246
	v_mov_b32_e32 v43, v247
	v_mov_b32_e32 v44, v248
	v_mov_b32_e32 v45, v249
	s_nop 0
	v_mov_b32_e32 v46, v250
	v_mov_b32_e32 v47, v251
	v_mov_b32_e32 v48, v252
	v_mov_b32_e32 v49, v253
	s_waitcnt lgkmcnt(0)
	v_cndmask_b32_e64 v28, v45, 1.0, s[4:5]
	v_cndmask_b32_e64 v29, v44, 1.0, s[4:5]
	v_cndmask_b32_e64 v34, v43, 1.0, s[4:5]
	v_cndmask_b32_e64 v35, v42, 1.0, s[4:5]
	v_cndmask_b32_e64 v42, v49, 1.0, s[4:5]
	v_cndmask_b32_e64 v43, v48, 1.0, s[4:5]
	v_cndmask_b32_e64 v44, v47, 1.0, s[4:5]
	v_cndmask_b32_e64 v45, v46, 1.0, s[4:5]
	v_mul_f32_e32 v35, v41, v35
	v_mul_f32_e32 v34, v41, v34
	v_mul_f32_e32 v29, v41, v29
	v_mul_f32_e32 v28, v41, v28
	v_mul_f32_e32 v45, v41, v45
	v_mul_f32_e32 v44, v41, v44
	v_mul_f32_e32 v43, v41, v43
	v_mul_f32_e32 v41, v41, v42
	v_mul_f32_e32 v19, v35, v19
	v_mul_f32_e32 v18, v34, v18
	v_mul_f32_e32 v21, v29, v21
	v_mul_f32_e32 v20, v28, v20
	v_mul_f32_e32 v23, v45, v23
	v_mul_f32_e32 v22, v44, v22
	v_mul_f32_e32 v25, v43, v25
	v_mul_f32_e32 v24, v41, v24
	v_cvt_pk_bf16_f32 v18, v19, v18
	v_cvt_pk_bf16_f32 v19, v21, v20
	v_cvt_pk_bf16_f32 v20, v23, v22
	v_cvt_pk_bf16_f32 v21, v25, v24
	ds_write_b128 v254, v[18:21] offset:112
	s_waitcnt lgkmcnt(0)
	ds_read_b128 v[114:117], v189
	ds_read_b128 v[118:121], v189 offset:1024
	ds_read_b128 v[122:125], v189 offset:2048
	ds_read_b128 v[126:129], v189 offset:3072
	ds_read_b128 v[130:133], v189 offset:4096
	ds_read_b128 v[134:137], v189 offset:5120
	ds_read_b128 v[138:141], v189 offset:6144
	ds_read_b128 v[142:145], v189 offset:7168
	s_waitcnt lgkmcnt(0)
	global_store_dwordx4 v188, v[114:117], s[64:65]
	global_store_dwordx4 v188, v[118:121], s[64:65] offset:1024
	global_store_dwordx4 v188, v[122:125], s[64:65] offset:2048
	global_store_dwordx4 v188, v[126:129], s[64:65] offset:3072
	global_store_dwordx4 v188, v[130:133], s[66:67]
	global_store_dwordx4 v188, v[134:137], s[66:67] offset:1024
	global_store_dwordx4 v188, v[138:141], s[66:67] offset:2048
	global_store_dwordx4 v188, v[142:145], s[66:67] offset:3072
	flat_load_dwordx4 v[18:21], v[36:37] offset:512
	s_nop 0
	flat_load_dwordx4 v[22:25], v[36:37] offset:640
	flat_load_dwordx4 v[42:45], v[36:37] offset:528
	s_nop 0
	flat_load_dwordx4 v[34:37], v[36:37] offset:656
	v_mov_b32_e32 v28, v100
	v_mov_b32_e32 v29, v32
	v_mov_b32_e32 v32, v101
	v_mov_b32_e32 v46, v102
	v_mov_b32_e32 v47, v26
	v_mov_b32_e32 v26, v103
	v_mov_b32_e32 v48, v104
	v_mov_b32_e32 v49, v58
	v_mov_b32_e32 v58, v105
	v_pk_mul_f32 v[28:29], v[40:41], v[28:29] op_sel_hi:[0,1]
	v_pk_mul_f32 v[30:31], v[40:41], v[30:31] op_sel_hi:[0,1]
	v_pk_mul_f32 v[32:33], v[40:41], v[32:33] op_sel_hi:[0,1]
	v_pk_mul_f32 v[46:47], v[40:41], v[46:47] op_sel_hi:[0,1]
	v_pk_mul_f32 v[26:27], v[40:41], v[26:27] op_sel_hi:[0,1]
	v_pk_mul_f32 v[48:49], v[40:41], v[48:49] op_sel_hi:[0,1]
	v_pk_mul_f32 v[50:51], v[40:41], v[58:59] op_sel_hi:[0,1]
	v_pk_mul_f32 v[40:41], v[40:41], v[60:61] op_sel_hi:[0,1]
	s_waitcnt vmcnt(0) lgkmcnt(0)
	v_mov_b32_e32 v52, v18
	v_mov_b32_e32 v53, v22
	v_mov_b32_e32 v22, v19
	v_mov_b32_e32 v18, v20
	v_mov_b32_e32 v19, v24
	v_mov_b32_e32 v24, v21
	v_mov_b32_e32 v20, v42
	v_mov_b32_e32 v21, v34
	v_mov_b32_e32 v34, v43
	v_mov_b32_e32 v42, v44
	v_mov_b32_e32 v43, v36
	v_mov_b32_e32 v36, v45
	v_pk_mul_f32 v[28:29], v[28:29], v[52:53]
	v_pk_mul_f32 v[22:23], v[30:31], v[22:23]
	v_pk_mul_f32 v[18:19], v[32:33], v[18:19]
	v_pk_mul_f32 v[24:25], v[46:47], v[24:25]
	v_pk_mul_f32 v[20:21], v[26:27], v[20:21]
	v_pk_mul_f32 v[26:27], v[48:49], v[34:35]
	v_pk_mul_f32 v[30:31], v[50:51], v[42:43]
	v_pk_mul_f32 v[32:33], v[40:41], v[36:37]
	v_pk_mul_f32 v[34:35], v[90:91], v[28:29]
	v_pk_mul_f32 v[14:15], v[14:15], v[22:23]
	v_pk_mul_f32 v[10:11], v[10:11], v[22:23]
	v_pk_mul_f32 v[22:23], v[88:89], v[18:19]
	v_pk_mul_f32 v[18:19], v[94:95], v[18:19]
	v_pk_mul_f32 v[16:17], v[16:17], v[24:25]
	v_pk_mul_f32 v[12:13], v[12:13], v[24:25]
	v_pk_mul_f32 v[24:25], v[86:87], v[20:21]
	v_pk_mul_f32 v[6:7], v[6:7], v[26:27]
	v_pk_mul_f32 v[2:3], v[2:3], v[26:27]
	v_pk_mul_f32 v[26:27], v[84:85], v[30:31]
	v_pk_mul_f32 v[8:9], v[8:9], v[32:33]
	v_pk_mul_f32 v[4:5], v[4:5], v[32:33]
	v_pk_mul_f32 v[28:29], v[92:93], v[28:29]
	v_pk_mul_f32 v[20:21], v[96:97], v[20:21]
	v_pk_mul_f32 v[30:31], v[98:99], v[30:31]
	v_sub_f32_e32 v32, v34, v35
	v_sub_f32_e32 v14, v14, v15
	v_add_f32_e32 v10, v10, v11
	v_sub_f32_e32 v11, v22, v23
	v_add_f32_e32 v15, v18, v19
	v_sub_f32_e32 v16, v16, v17
	v_add_f32_e32 v12, v12, v13
	v_sub_f32_e32 v13, v24, v25
	v_sub_f32_e32 v6, v6, v7
	v_add_f32_e32 v7, v2, v3
	v_sub_f32_e32 v18, v26, v27
	v_sub_f32_e32 v8, v8, v9
	v_add_f32_e32 v9, v4, v5
	v_cvt_pk_bf16_f32 v2, v32, v14
	v_cvt_pk_bf16_f32 v3, v11, v16
	v_cvt_pk_bf16_f32 v4, v13, v6
	v_cvt_pk_bf16_f32 v5, v18, v8
	v_add_f32_e32 v28, v28, v29
	v_add_f32_e32 v17, v20, v21
	v_add_f32_e32 v19, v30, v31
	global_store_dwordx4 v[38:39], v[2:5], off
	s_nop 1
	v_cvt_pk_bf16_f32 v2, v28, v10
	v_cvt_pk_bf16_f32 v3, v15, v12
	v_cvt_pk_bf16_f32 v4, v17, v7
	v_cvt_pk_bf16_f32 v5, v19, v9
	global_store_dwordx4 v[38:39], v[2:5], off offset:64
	s_cbranch_scc1 .LBB0_275
